# G3 SwiGLU epilogue: hoist 8 row-sum loads to top, single vmcnt wait, stores no longer waited
# speedup vs baseline: 1.0014x; 1.0014x over previous
.LBB0_963:
	v_lshl_add_u32 v140, s51, 8, v144
	v_ashrrev_i32_e32 v141, 31, v140
	v_lshl_add_u64 v[142:143], v[140:141], 2, s[6:7]
	global_load_dword v200, v[142:143], off
	global_load_dword v201, v[142:143], off offset:64
	global_load_dword v202, v[142:143], off offset:128
	global_load_dword v203, v[142:143], off offset:192
	global_load_dword v204, v[142:143], off offset:512
	global_load_dword v205, v[142:143], off offset:576
	global_load_dword v206, v[142:143], off offset:640
	global_load_dword v207, v[142:143], off offset:704
	v_pk_mul_f32 v[150:151], v[118:119], v[122:123]
	v_lshl_or_b32 v148, s50, 7, v146
	v_pk_mul_f32 v[152:153], v[116:117], v[120:121]
	v_mov_b64_e32 v[120:121], s[8:9]
	v_ashrrev_i32_e32 v149, 31, v148
	v_mad_i64_i32 v[154:155], s[14:15], v140, s53, v[120:121]
	v_pk_mul_f32 v[128:129], v[124:125], v[128:129]
	v_pk_mul_f32 v[130:131], v[126:127], v[130:131]
	v_pk_mul_f32 v[102:103], v[106:107], v[102:103]
	v_pk_mul_f32 v[100:101], v[104:105], v[100:101]
	v_pk_mul_f32 v[114:115], v[110:111], v[114:115]
	v_pk_mul_f32 v[112:113], v[108:109], v[112:113]
	v_pk_mul_f32 v[86:87], v[90:91], v[86:87]
	v_pk_mul_f32 v[84:85], v[88:89], v[84:85]
	v_pk_mul_f32 v[98:99], v[94:95], v[98:99]
	v_pk_mul_f32 v[96:97], v[92:93], v[96:97]
	v_pk_mul_f32 v[70:71], v[74:75], v[70:71]
	v_pk_mul_f32 v[68:69], v[72:73], v[68:69]
	v_pk_mul_f32 v[82:83], v[78:79], v[82:83]
	v_pk_mul_f32 v[80:81], v[76:77], v[80:81]
	v_pk_mul_f32 v[54:55], v[58:59], v[54:55]
	v_pk_mul_f32 v[52:53], v[56:57], v[52:53]
	v_pk_mul_f32 v[66:67], v[62:63], v[66:67]
	v_pk_mul_f32 v[64:65], v[60:61], v[64:65]
	v_pk_mul_f32 v[38:39], v[42:43], v[38:39]
	v_pk_mul_f32 v[36:37], v[40:41], v[36:37]
	v_pk_mul_f32 v[50:51], v[46:47], v[50:51]
	v_pk_mul_f32 v[48:49], v[44:45], v[48:49]
	v_pk_mul_f32 v[22:23], v[26:27], v[22:23]
	v_pk_mul_f32 v[20:21], v[24:25], v[20:21]
	v_pk_mul_f32 v[34:35], v[30:31], v[34:35]
	v_pk_mul_f32 v[32:33], v[28:29], v[32:33]
	v_pk_mul_f32 v[10:11], v[6:7], v[10:11]
	v_pk_mul_f32 v[8:9], v[4:5], v[8:9]
	v_pk_mul_f32 v[18:19], v[14:15], v[18:19]
	v_pk_mul_f32 v[16:17], v[12:13], v[16:17]
	s_andn2_b64 vcc, exec, s[0:1]
	s_mov_b64 s[0:1], -1
	s_waitcnt vmcnt(0)
	v_fmamk_f32 v122, v200, 0x3a800000, v195
	v_rsq_f32_e32 v141, v122
	v_lshlrev_b64 v[122:123], 1, v[148:149]
	v_lshl_add_u64 v[148:149], v[154:155], 0, v[122:123]
	v_mul_f32_e32 v154, 0xbfb8aa3b, v141
	v_pk_mul_f32 v[124:125], v[124:125], v[154:155] op_sel_hi:[1,0]
	v_pk_mul_f32 v[118:119], v[118:119], v[154:155] op_sel_hi:[1,0]
	v_pk_mul_f32 v[116:117], v[116:117], v[154:155] op_sel_hi:[1,0]
	v_pk_mul_f32 v[126:127], v[126:127], v[154:155] op_sel_hi:[1,0]
	v_exp_f32_e32 v124, v124
	v_exp_f32_e32 v125, v125
	v_exp_f32_e32 v116, v116
	v_exp_f32_e32 v118, v118
	v_exp_f32_e32 v119, v119
	v_exp_f32_e32 v117, v117
	v_exp_f32_e32 v126, v126
	v_exp_f32_e32 v127, v127
	v_pk_add_f32 v[124:125], v[124:125], 1.0 op_sel_hi:[1,0]
	v_pk_add_f32 v[118:119], v[118:119], 1.0 op_sel_hi:[1,0]
	v_pk_add_f32 v[116:117], v[116:117], 1.0 op_sel_hi:[1,0]
	v_pk_add_f32 v[126:127], v[126:127], 1.0 op_sel_hi:[1,0]
	v_rcp_f32_e32 v124, v124
	v_rcp_f32_e32 v125, v125
	v_rcp_f32_e32 v116, v116
	v_rcp_f32_e32 v117, v117
	v_rcp_f32_e32 v118, v118
	v_rcp_f32_e32 v119, v119
	v_rcp_f32_e32 v126, v126
	v_rcp_f32_e32 v127, v127
	v_mul_f32_e32 v172, v141, v141
	v_pk_mul_f32 v[124:125], v[172:173], v[124:125] op_sel_hi:[0,1]
	v_pk_mul_f32 v[116:117], v[172:173], v[116:117] op_sel_hi:[0,1]
	v_pk_mul_f32 v[118:119], v[172:173], v[118:119] op_sel_hi:[0,1]
	v_pk_mul_f32 v[126:127], v[172:173], v[126:127] op_sel_hi:[0,1]
	v_pk_mul_f32 v[124:125], v[128:129], v[124:125]
	v_pk_mul_f32 v[128:129], v[150:151], v[118:119]
	v_pk_mul_f32 v[118:119], v[152:153], v[116:117]
	v_pk_mul_f32 v[126:127], v[130:131], v[126:127]
	v_cvt_pk_bf16_f32 v116, v124, v125
	s_nop 0
	v_cvt_pk_bf16_f32 v117, v126, v127
	v_cvt_pk_bf16_f32 v118, v118, v119
	v_cvt_pk_bf16_f32 v119, v128, v129
	global_store_dwordx4 v[148:149], v[116:119], off
	s_nop 0
	s_nop 0
	v_or_b32_e32 v117, 16, v140
	v_fmamk_f32 v116, v201, 0x3a800000, v195
	v_rsq_f32_e32 v119, v116
	v_mad_i64_i32 v[116:117], s[14:15], v117, s53, v[120:121]
	v_lshl_add_u64 v[116:117], v[116:117], 0, v[122:123]
	v_mul_f32_e32 v118, 0xbfb8aa3b, v119
	v_pk_mul_f32 v[106:107], v[106:107], v[118:119] op_sel_hi:[1,0]
	v_pk_mul_f32 v[104:105], v[104:105], v[118:119] op_sel_hi:[1,0]
	v_pk_mul_f32 v[110:111], v[110:111], v[118:119] op_sel_hi:[1,0]
	v_pk_mul_f32 v[108:109], v[108:109], v[118:119] op_sel_hi:[1,0]
	v_exp_f32_e32 v104, v104
	v_exp_f32_e32 v106, v106
	v_exp_f32_e32 v107, v107
	v_exp_f32_e32 v105, v105
	v_exp_f32_e32 v108, v108
	v_exp_f32_e32 v109, v109
	v_exp_f32_e32 v110, v110
	v_exp_f32_e32 v111, v111
	v_pk_add_f32 v[106:107], v[106:107], 1.0 op_sel_hi:[1,0]
	v_pk_add_f32 v[104:105], v[104:105], 1.0 op_sel_hi:[1,0]
	v_pk_add_f32 v[108:109], v[108:109], 1.0 op_sel_hi:[1,0]
	v_pk_add_f32 v[110:111], v[110:111], 1.0 op_sel_hi:[1,0]
	v_rcp_f32_e32 v104, v104
	v_rcp_f32_e32 v105, v105
	v_rcp_f32_e32 v106, v106
	v_rcp_f32_e32 v107, v107
	v_rcp_f32_e32 v108, v108
	v_rcp_f32_e32 v109, v109
	v_rcp_f32_e32 v110, v110
	v_rcp_f32_e32 v111, v111
	v_mul_f32_e32 v124, v119, v119
	v_pk_mul_f32 v[104:105], v[124:125], v[104:105] op_sel_hi:[0,1]
	v_pk_mul_f32 v[106:107], v[124:125], v[106:107] op_sel_hi:[0,1]
	v_pk_mul_f32 v[108:109], v[124:125], v[108:109] op_sel_hi:[0,1]
	v_pk_mul_f32 v[110:111], v[124:125], v[110:111] op_sel_hi:[0,1]
	v_pk_mul_f32 v[106:107], v[102:103], v[106:107]
	v_pk_mul_f32 v[102:103], v[100:101], v[104:105]
	v_pk_mul_f32 v[110:111], v[114:115], v[110:111]
	v_pk_mul_f32 v[108:109], v[112:113], v[108:109]
	s_nop 0
	v_cvt_pk_bf16_f32 v100, v108, v109
	v_cvt_pk_bf16_f32 v101, v110, v111
	v_cvt_pk_bf16_f32 v102, v102, v103
	v_cvt_pk_bf16_f32 v103, v106, v107
	global_store_dwordx4 v[116:117], v[100:103], off
	s_nop 0
	s_nop 0
	v_or_b32_e32 v101, 32, v140
	v_fmamk_f32 v100, v202, 0x3a800000, v195
	v_rsq_f32_e32 v103, v100
	v_mad_i64_i32 v[100:101], s[14:15], v101, s53, v[120:121]
	v_lshl_add_u64 v[100:101], v[100:101], 0, v[122:123]
	v_mul_f32_e32 v102, 0xbfb8aa3b, v103
	v_pk_mul_f32 v[90:91], v[90:91], v[102:103] op_sel_hi:[1,0]
	v_pk_mul_f32 v[88:89], v[88:89], v[102:103] op_sel_hi:[1,0]
	v_pk_mul_f32 v[94:95], v[94:95], v[102:103] op_sel_hi:[1,0]
	v_pk_mul_f32 v[92:93], v[92:93], v[102:103] op_sel_hi:[1,0]
	v_exp_f32_e32 v88, v88
	v_exp_f32_e32 v90, v90
	v_exp_f32_e32 v91, v91
	v_exp_f32_e32 v89, v89
	v_exp_f32_e32 v92, v92
	v_exp_f32_e32 v93, v93
	v_exp_f32_e32 v94, v94
	v_exp_f32_e32 v95, v95
	v_pk_add_f32 v[90:91], v[90:91], 1.0 op_sel_hi:[1,0]
	v_pk_add_f32 v[88:89], v[88:89], 1.0 op_sel_hi:[1,0]
	v_pk_add_f32 v[92:93], v[92:93], 1.0 op_sel_hi:[1,0]
	v_pk_add_f32 v[94:95], v[94:95], 1.0 op_sel_hi:[1,0]
	v_rcp_f32_e32 v88, v88
	v_rcp_f32_e32 v89, v89
	v_rcp_f32_e32 v90, v90
	v_rcp_f32_e32 v91, v91
	v_rcp_f32_e32 v92, v92
	v_rcp_f32_e32 v93, v93
	v_rcp_f32_e32 v94, v94
	v_rcp_f32_e32 v95, v95
	v_mul_f32_e32 v104, v103, v103
	v_pk_mul_f32 v[88:89], v[104:105], v[88:89] op_sel_hi:[0,1]
	v_pk_mul_f32 v[90:91], v[104:105], v[90:91] op_sel_hi:[0,1]
	v_pk_mul_f32 v[92:93], v[104:105], v[92:93] op_sel_hi:[0,1]
	v_pk_mul_f32 v[94:95], v[104:105], v[94:95] op_sel_hi:[0,1]
	v_pk_mul_f32 v[90:91], v[86:87], v[90:91]
	v_pk_mul_f32 v[86:87], v[84:85], v[88:89]
	v_pk_mul_f32 v[94:95], v[98:99], v[94:95]
	v_pk_mul_f32 v[92:93], v[96:97], v[92:93]
	s_nop 0
	v_cvt_pk_bf16_f32 v84, v92, v93
	v_cvt_pk_bf16_f32 v85, v94, v95
	v_cvt_pk_bf16_f32 v86, v86, v87
	v_cvt_pk_bf16_f32 v87, v90, v91
	global_store_dwordx4 v[100:101], v[84:87], off
	s_nop 0
	s_nop 0
	v_or_b32_e32 v85, 48, v140
	v_fmamk_f32 v84, v203, 0x3a800000, v195
	v_rsq_f32_e32 v87, v84
	v_mad_i64_i32 v[84:85], s[14:15], v85, s53, v[120:121]
	v_lshl_add_u64 v[84:85], v[84:85], 0, v[122:123]
	v_mul_f32_e32 v86, 0xbfb8aa3b, v87
	v_pk_mul_f32 v[74:75], v[74:75], v[86:87] op_sel_hi:[1,0]
	v_pk_mul_f32 v[72:73], v[72:73], v[86:87] op_sel_hi:[1,0]
	v_pk_mul_f32 v[78:79], v[78:79], v[86:87] op_sel_hi:[1,0]
	v_pk_mul_f32 v[76:77], v[76:77], v[86:87] op_sel_hi:[1,0]
	v_exp_f32_e32 v72, v72
	v_exp_f32_e32 v74, v74
	v_exp_f32_e32 v75, v75
	v_exp_f32_e32 v73, v73
	v_exp_f32_e32 v76, v76
	v_exp_f32_e32 v77, v77
	v_exp_f32_e32 v78, v78
	v_exp_f32_e32 v79, v79
	v_pk_add_f32 v[74:75], v[74:75], 1.0 op_sel_hi:[1,0]
	v_pk_add_f32 v[72:73], v[72:73], 1.0 op_sel_hi:[1,0]
	v_pk_add_f32 v[76:77], v[76:77], 1.0 op_sel_hi:[1,0]
	v_pk_add_f32 v[78:79], v[78:79], 1.0 op_sel_hi:[1,0]
	v_rcp_f32_e32 v72, v72
	v_rcp_f32_e32 v73, v73
	v_rcp_f32_e32 v74, v74
	v_rcp_f32_e32 v75, v75
	v_rcp_f32_e32 v76, v76
	v_rcp_f32_e32 v77, v77
	v_rcp_f32_e32 v78, v78
	v_rcp_f32_e32 v79, v79
	v_mul_f32_e32 v88, v87, v87
	v_pk_mul_f32 v[72:73], v[88:89], v[72:73] op_sel_hi:[0,1]
	v_pk_mul_f32 v[74:75], v[88:89], v[74:75] op_sel_hi:[0,1]
	v_pk_mul_f32 v[76:77], v[88:89], v[76:77] op_sel_hi:[0,1]
	v_pk_mul_f32 v[78:79], v[88:89], v[78:79] op_sel_hi:[0,1]
	v_pk_mul_f32 v[74:75], v[70:71], v[74:75]
	v_pk_mul_f32 v[70:71], v[68:69], v[72:73]
	v_pk_mul_f32 v[78:79], v[82:83], v[78:79]
	v_pk_mul_f32 v[76:77], v[80:81], v[76:77]
	s_nop 0
	v_cvt_pk_bf16_f32 v68, v76, v77
	v_cvt_pk_bf16_f32 v69, v78, v79
	v_cvt_pk_bf16_f32 v70, v70, v71
	v_cvt_pk_bf16_f32 v71, v74, v75
	global_store_dwordx4 v[84:85], v[68:71], off
	s_nop 0
	s_nop 0
	v_add_u32_e32 v69, 0x80, v140
	v_fmamk_f32 v68, v204, 0x3a800000, v195
	v_rsq_f32_e32 v71, v68
	v_mad_i64_i32 v[68:69], s[14:15], v69, s53, v[120:121]
	v_lshl_add_u64 v[68:69], v[68:69], 0, v[122:123]
	v_mul_f32_e32 v70, 0xbfb8aa3b, v71
	v_pk_mul_f32 v[58:59], v[58:59], v[70:71] op_sel_hi:[1,0]
	v_pk_mul_f32 v[56:57], v[56:57], v[70:71] op_sel_hi:[1,0]
	v_pk_mul_f32 v[62:63], v[62:63], v[70:71] op_sel_hi:[1,0]
	v_pk_mul_f32 v[60:61], v[60:61], v[70:71] op_sel_hi:[1,0]
	v_exp_f32_e32 v56, v56
	v_exp_f32_e32 v58, v58
	v_exp_f32_e32 v59, v59
	v_exp_f32_e32 v57, v57
	v_exp_f32_e32 v60, v60
	v_exp_f32_e32 v61, v61
	v_exp_f32_e32 v62, v62
	v_exp_f32_e32 v63, v63
	v_pk_add_f32 v[58:59], v[58:59], 1.0 op_sel_hi:[1,0]
	v_pk_add_f32 v[56:57], v[56:57], 1.0 op_sel_hi:[1,0]
	v_pk_add_f32 v[60:61], v[60:61], 1.0 op_sel_hi:[1,0]
	v_pk_add_f32 v[62:63], v[62:63], 1.0 op_sel_hi:[1,0]
	v_rcp_f32_e32 v56, v56
	v_rcp_f32_e32 v57, v57
	v_rcp_f32_e32 v58, v58
	v_rcp_f32_e32 v59, v59
	v_rcp_f32_e32 v60, v60
	v_rcp_f32_e32 v61, v61
	v_rcp_f32_e32 v62, v62
	v_rcp_f32_e32 v63, v63
	v_mul_f32_e32 v72, v71, v71
	v_pk_mul_f32 v[56:57], v[72:73], v[56:57] op_sel_hi:[0,1]
	v_pk_mul_f32 v[58:59], v[72:73], v[58:59] op_sel_hi:[0,1]
	v_pk_mul_f32 v[60:61], v[72:73], v[60:61] op_sel_hi:[0,1]
	v_pk_mul_f32 v[62:63], v[72:73], v[62:63] op_sel_hi:[0,1]
	v_pk_mul_f32 v[58:59], v[54:55], v[58:59]
	v_pk_mul_f32 v[54:55], v[52:53], v[56:57]
	v_pk_mul_f32 v[62:63], v[66:67], v[62:63]
	v_pk_mul_f32 v[60:61], v[64:65], v[60:61]
	s_nop 0
	v_cvt_pk_bf16_f32 v52, v60, v61
	v_cvt_pk_bf16_f32 v53, v62, v63
	v_cvt_pk_bf16_f32 v54, v54, v55
	v_cvt_pk_bf16_f32 v55, v58, v59
	global_store_dwordx4 v[68:69], v[52:55], off
	s_nop 0
	s_nop 0
	v_add_u32_e32 v53, 0x90, v140
	v_fmamk_f32 v52, v205, 0x3a800000, v195
	v_rsq_f32_e32 v55, v52
	v_mad_i64_i32 v[52:53], s[14:15], v53, s53, v[120:121]
	v_lshl_add_u64 v[52:53], v[52:53], 0, v[122:123]
	v_mul_f32_e32 v54, 0xbfb8aa3b, v55
	v_pk_mul_f32 v[42:43], v[42:43], v[54:55] op_sel_hi:[1,0]
	v_pk_mul_f32 v[40:41], v[40:41], v[54:55] op_sel_hi:[1,0]
	v_pk_mul_f32 v[46:47], v[46:47], v[54:55] op_sel_hi:[1,0]
	v_pk_mul_f32 v[44:45], v[44:45], v[54:55] op_sel_hi:[1,0]
	v_exp_f32_e32 v40, v40
	v_exp_f32_e32 v42, v42
	v_exp_f32_e32 v43, v43
	v_exp_f32_e32 v41, v41
	v_exp_f32_e32 v44, v44
	v_exp_f32_e32 v45, v45
	v_exp_f32_e32 v46, v46
	v_exp_f32_e32 v47, v47
	v_pk_add_f32 v[42:43], v[42:43], 1.0 op_sel_hi:[1,0]
	v_pk_add_f32 v[40:41], v[40:41], 1.0 op_sel_hi:[1,0]
	v_pk_add_f32 v[44:45], v[44:45], 1.0 op_sel_hi:[1,0]
	v_pk_add_f32 v[46:47], v[46:47], 1.0 op_sel_hi:[1,0]
	v_rcp_f32_e32 v40, v40
	v_rcp_f32_e32 v41, v41
	v_rcp_f32_e32 v42, v42
	v_rcp_f32_e32 v43, v43
	v_rcp_f32_e32 v44, v44
	v_rcp_f32_e32 v45, v45
	v_rcp_f32_e32 v46, v46
	v_rcp_f32_e32 v47, v47
	v_mul_f32_e32 v56, v55, v55
	v_pk_mul_f32 v[40:41], v[56:57], v[40:41] op_sel_hi:[0,1]
	v_pk_mul_f32 v[42:43], v[56:57], v[42:43] op_sel_hi:[0,1]
	v_pk_mul_f32 v[44:45], v[56:57], v[44:45] op_sel_hi:[0,1]
	v_pk_mul_f32 v[46:47], v[56:57], v[46:47] op_sel_hi:[0,1]
	v_pk_mul_f32 v[42:43], v[38:39], v[42:43]
	v_pk_mul_f32 v[38:39], v[36:37], v[40:41]
	v_pk_mul_f32 v[46:47], v[50:51], v[46:47]
	v_pk_mul_f32 v[44:45], v[48:49], v[44:45]
	s_nop 0
	v_cvt_pk_bf16_f32 v36, v44, v45
	v_cvt_pk_bf16_f32 v37, v46, v47
	v_cvt_pk_bf16_f32 v38, v38, v39
	v_cvt_pk_bf16_f32 v39, v42, v43
	global_store_dwordx4 v[52:53], v[36:39], off
	s_nop 0
	s_nop 0
	v_add_u32_e32 v37, 0xa0, v140
	v_fmamk_f32 v36, v206, 0x3a800000, v195
	v_rsq_f32_e32 v39, v36
	v_mad_i64_i32 v[36:37], s[14:15], v37, s53, v[120:121]
	v_lshl_add_u64 v[36:37], v[36:37], 0, v[122:123]
	v_mul_f32_e32 v38, 0xbfb8aa3b, v39
	v_pk_mul_f32 v[26:27], v[26:27], v[38:39] op_sel_hi:[1,0]
	v_pk_mul_f32 v[24:25], v[24:25], v[38:39] op_sel_hi:[1,0]
	v_pk_mul_f32 v[30:31], v[30:31], v[38:39] op_sel_hi:[1,0]
	v_pk_mul_f32 v[28:29], v[28:29], v[38:39] op_sel_hi:[1,0]
	v_exp_f32_e32 v24, v24
	v_exp_f32_e32 v26, v26
	v_exp_f32_e32 v27, v27
	v_exp_f32_e32 v25, v25
	v_exp_f32_e32 v28, v28
	v_exp_f32_e32 v29, v29
	v_exp_f32_e32 v30, v30
	v_exp_f32_e32 v31, v31
	v_pk_add_f32 v[26:27], v[26:27], 1.0 op_sel_hi:[1,0]
	v_pk_add_f32 v[24:25], v[24:25], 1.0 op_sel_hi:[1,0]
	v_pk_add_f32 v[28:29], v[28:29], 1.0 op_sel_hi:[1,0]
	v_pk_add_f32 v[30:31], v[30:31], 1.0 op_sel_hi:[1,0]
	v_rcp_f32_e32 v24, v24
	v_rcp_f32_e32 v25, v25
	v_rcp_f32_e32 v26, v26
	v_rcp_f32_e32 v27, v27
	v_rcp_f32_e32 v28, v28
	v_rcp_f32_e32 v29, v29
	v_rcp_f32_e32 v30, v30
	v_rcp_f32_e32 v31, v31
	v_mul_f32_e32 v40, v39, v39
	v_pk_mul_f32 v[24:25], v[40:41], v[24:25] op_sel_hi:[0,1]
	v_pk_mul_f32 v[26:27], v[40:41], v[26:27] op_sel_hi:[0,1]
	v_pk_mul_f32 v[28:29], v[40:41], v[28:29] op_sel_hi:[0,1]
	v_pk_mul_f32 v[30:31], v[40:41], v[30:31] op_sel_hi:[0,1]
	v_pk_mul_f32 v[26:27], v[22:23], v[26:27]
	v_pk_mul_f32 v[22:23], v[20:21], v[24:25]
	v_pk_mul_f32 v[30:31], v[34:35], v[30:31]
	v_pk_mul_f32 v[28:29], v[32:33], v[28:29]
	s_nop 0
	v_cvt_pk_bf16_f32 v20, v28, v29
	v_cvt_pk_bf16_f32 v21, v30, v31
	v_cvt_pk_bf16_f32 v22, v22, v23
	v_cvt_pk_bf16_f32 v23, v26, v27
	global_store_dwordx4 v[36:37], v[20:23], off
	s_nop 0
	s_nop 0
	v_add_u32_e32 v21, 0xb0, v140
	v_fmamk_f32 v20, v207, 0x3a800000, v195
	v_rsq_f32_e32 v23, v20
	v_mad_i64_i32 v[20:21], s[14:15], v21, s53, v[120:121]
	v_lshl_add_u64 v[20:21], v[20:21], 0, v[122:123]
	v_mul_f32_e32 v22, 0xbfb8aa3b, v23
	v_pk_mul_f32 v[6:7], v[6:7], v[22:23] op_sel_hi:[1,0]
	v_pk_mul_f32 v[4:5], v[4:5], v[22:23] op_sel_hi:[1,0]
	v_pk_mul_f32 v[14:15], v[14:15], v[22:23] op_sel_hi:[1,0]
	v_pk_mul_f32 v[12:13], v[12:13], v[22:23] op_sel_hi:[1,0]
	v_exp_f32_e32 v4, v4
	v_exp_f32_e32 v6, v6
	v_exp_f32_e32 v7, v7
	v_exp_f32_e32 v5, v5
	v_exp_f32_e32 v12, v12
	v_exp_f32_e32 v13, v13
	v_exp_f32_e32 v14, v14
	v_exp_f32_e32 v15, v15
	v_pk_add_f32 v[6:7], v[6:7], 1.0 op_sel_hi:[1,0]
	v_pk_add_f32 v[4:5], v[4:5], 1.0 op_sel_hi:[1,0]
	v_pk_add_f32 v[12:13], v[12:13], 1.0 op_sel_hi:[1,0]
	v_pk_add_f32 v[14:15], v[14:15], 1.0 op_sel_hi:[1,0]
	v_rcp_f32_e32 v4, v4
	v_rcp_f32_e32 v5, v5
	v_rcp_f32_e32 v6, v6
	v_rcp_f32_e32 v7, v7
	v_rcp_f32_e32 v12, v12
	v_rcp_f32_e32 v13, v13
	v_rcp_f32_e32 v14, v14
	v_rcp_f32_e32 v15, v15
	v_mul_f32_e32 v24, v23, v23
	v_pk_mul_f32 v[4:5], v[24:25], v[4:5] op_sel_hi:[0,1]
	v_pk_mul_f32 v[6:7], v[24:25], v[6:7] op_sel_hi:[0,1]
	v_pk_mul_f32 v[12:13], v[24:25], v[12:13] op_sel_hi:[0,1]
	v_pk_mul_f32 v[14:15], v[24:25], v[14:15] op_sel_hi:[0,1]
	v_pk_mul_f32 v[10:11], v[10:11], v[6:7]
	v_pk_mul_f32 v[6:7], v[8:9], v[4:5]
	v_pk_mul_f32 v[14:15], v[18:19], v[14:15]
	v_pk_mul_f32 v[12:13], v[16:17], v[12:13]
	s_nop 0
	v_cvt_pk_bf16_f32 v4, v12, v13
	v_cvt_pk_bf16_f32 v5, v14, v15
	v_cvt_pk_bf16_f32 v6, v6, v7
	v_cvt_pk_bf16_f32 v7, v10, v11
	global_store_dwordx4 v[20:21], v[4:7], off
	s_cbranch_vccnz .LBB0_956
	s_andn2_b64 vcc, exec, s[4:5]
	s_cbranch_vccnz .LBB0_955
	s_barrier
	s_branch .LBB0_955
